# first phase boundary uses the XCD barrier instead of cooperative-groups grid sync
# speedup vs baseline: 1.0296x; 1.0002x over previous
; #define LAS __attribute__((address_space(3)))
; DI unsigned xb_xcc_id() { return (unsigned)__builtin_amdgcn_s_getreg((3 << 11) | 20) & 0xFu; }
; DI void xcd_barrier(const XcdBarrier& b) {
;     asm volatile("s_waitcnt vmcnt(0)" ::: "memory");
;     __syncthreads();
;     if (threadIdx.x == 0) {
;         unsigned* bar = b.bar;
;         __builtin_amdgcn_s_waitcnt(0);
;         unsigned nloc = b.st[0], nx = b.st[1];
;         if (nloc == 0u) { xcd_barrier_complete(bar, b.x, nloc, nx); b.st[0] = nloc; b.st[1] = nx; }
; __global__ void __launch_bounds__(512) mk_fwd(Args a) {
;     ...
;         if (ph > a.ph_lo) { if (ph == 1) grid.sync(); else { XcdBarrier xbar; xbar.bar = (unsigned*)(a.ws + WS_BAR); xbar.x = xb_xcc_id(); xbar.st = (volatile LAS unsigned*)(lds + LDS_MAIN); xcd_barrier(xbar); } }
.LBB0_9:
	s_cmp_le_i32 s62, s82
	s_cbranch_scc1 .LBB0_77
	s_mov_b64 s[8:9], -1
	s_getreg_b32 s2, hwreg(HW_REG_XCC_ID, 0, 4)
	s_waitcnt vmcnt(0)
	s_barrier
	s_mov_b64 s[8:9], exec
	v_readlane_b32 s10, v253, 2
	v_readlane_b32 s11, v253, 3
	s_and_b64 s[10:11], s[8:9], s[10:11]
	s_mov_b64 exec, s[10:11]
	s_cbranch_execz .LBB0_63
	v_readlane_b32 s5, v254, 57
	s_waitcnt vmcnt(0) expcnt(0) lgkmcnt(0)
	s_and_b32 s2, s2, 15
	v_mov_b32_e32 v0, s5
	ds_read_b32 v2, v0
	v_readlane_b32 s5, v254, 58
	s_waitcnt lgkmcnt(0)
	v_cmp_ne_u32_e32 vcc, 0, v2
	v_mov_b32_e32 v0, s5
	ds_read_b32 v0, v0
	s_cbranch_vccnz .LBB0_27
	s_mov_b32 s5, 1
	s_branch .LBB0_15
